# loop-edge rotation in the diff loops: LDS base addresses for the next tile computed before the per-tile barrier; on top of the GEMM redundant-wait removal
# speedup vs baseline: 1.0060x; 1.0060x over previous
; #define MFMA32(a, b, c) __builtin_amdgcn_mfma_f32_32x32x16_bf16((a), (b), (c), 0, 0, 0)
; #define D_STORE(buf) do { *(LAS u32x4*)(lds + klds + (buf) * DK_BUF) = st0; *(LAS u32x4*)(lds + klds + (buf) * DK_BUF + 32 * DK_STR) = st1; *(LAS u32x4*)(lds + vlds + (buf) * DV_BUF) = st2; *(LAS u32x4*)(lds + vlds + (buf) * DV_BUF + 32 * DV_STR) = st3; } while (0)
; __device__ __forceinline__ void diff_unit(const Frame& F, int b, int h, int qi, float lam, int dry) {
;     ...
;             float ps = 0.f;
; #pragma unroll
;             for (int r = 0; r < 16; ++r) { s0[r] = __builtin_amdgcn_exp2f(s0[r] * LOG2E - ms); ps += s0[r]; }
;             if (!meta) {
; #pragma unroll
;                 for (int r = 0; r < 16; ++r) { s1[r] = __builtin_amdgcn_exp2f(s1[r] * LOG2E - ms); ps += s1[r]; }
;             }
;             lsum += ps;
;             __builtin_amdgcn_s_setprio(1);
;             { const bf16x8 pf = pack_step(s0, 0);
;               O[0] = MFMA32(vpre0, pf, O[0]); O[1] = MFMA32(vpre1, pf, O[1]); O[2] = MFMA32(vpre2, pf, O[2]); O[3] = MFMA32(vpre3, pf, O[3]); }
;     ...
;         if (it + 1 < nt) D_STORE((it + 1) & 1);
;         __syncthreads();
.LBB0_295:
	v_sub_f32_e32 v238, 0, v185
	v_sub_f32_e32 v239, 0, v185
	v_sub_f32_e32 v240, 0, v185
	v_sub_f32_e32 v241, 0, v185
	v_sub_f32_e32 v242, 0, v185
	v_sub_f32_e32 v243, 0, v185
	v_sub_f32_e32 v244, 0, v185
	v_sub_f32_e32 v245, 0, v185
	v_sub_f32_e32 v246, 0, v185
	v_sub_f32_e32 v247, 0, v185
	v_sub_f32_e32 v248, 0, v185
	v_sub_f32_e32 v249, 0, v185
	v_sub_f32_e32 v250, 0, v185
	v_sub_f32_e32 v251, 0, v185
	v_sub_f32_e32 v252, 0, v185
	v_sub_f32_e32 v253, 0, v185
	v_sub_f32_e32 v16, v16, v185
	v_exp_f32_e32 v16, v16
	v_sub_f32_e32 v17, v17, v185
	v_exp_f32_e32 v17, v17
	v_sub_f32_e32 v18, v18, v185
	v_exp_f32_e32 v18, v18
	v_sub_f32_e32 v19, v19, v185
	v_exp_f32_e32 v19, v19
	v_sub_f32_e32 v20, v20, v185
	v_add_f32_e32 v24, 0, v16
	v_exp_f32_e32 v20, v20
	v_sub_f32_e32 v21, v21, v185
	v_add_f32_e32 v24, v17, v24
	v_exp_f32_e32 v21, v21
	v_sub_f32_e32 v22, v22, v185
	v_add_f32_e32 v24, v18, v24
	v_exp_f32_e32 v22, v22
	v_sub_f32_e32 v23, v23, v185
	v_add_f32_e32 v24, v19, v24
	v_exp_f32_e32 v23, v23
	v_sub_f32_e32 v25, 0xff800000, v185
	v_add_f32_e32 v24, v20, v24
	v_exp_f32_e32 v25, v25
	v_add_f32_e32 v24, v21, v24
	v_add_f32_e32 v24, v22, v24
	v_add_f32_e32 v24, v23, v24
	v_add_f32_e32 v24, v25, v24
	v_add_f32_e32 v24, v25, v24
	v_add_f32_e32 v24, v25, v24
	v_add_f32_e32 v24, v25, v24
	s_mov_b64 s[2:3], 0x10000
	v_add_f32_e32 v24, v25, v24
	v_lshl_add_u64 v[200:201], v[188:189], 0, s[2:3]
	v_lshl_add_u64 v[202:203], v[190:191], 0, s[2:3]
	s_mov_b64 s[2:3], 0x8000
	s_lshl_b32 s1, s33, 1
	v_add_f32_e32 v24, v25, v24
	v_lshl_add_u64 v[192:193], v[188:189], 0, s[2:3]
	v_lshl_add_u64 v[196:197], v[190:191], 0, s[2:3]
	s_and_b32 s2, s1, 0x700
	s_and_b32 s1, s82, 15
	v_add_f32_e32 v24, v25, v24
	s_mov_b64 s[4:5], 0x18000
	v_lshl_add_u32 v153, s1, 7, v217
	s_lshl_b32 s1, s1, 18
	s_lshl_b32 s95, s90, 1
	v_add_f32_e32 v24, v25, v24
	v_mov_b32_e32 v2, v1
	v_mov_b32_e32 v3, v1
	v_mov_b32_e32 v4, v1
	v_mov_b32_e32 v5, v1
	v_mov_b32_e32 v6, v1
	v_mov_b32_e32 v7, v1
	v_mov_b32_e32 v8, v1
	v_mov_b32_e32 v9, v1
	v_mov_b32_e32 v10, v1
	v_mov_b32_e32 v11, v1
	v_mov_b32_e32 v12, v1
	v_mov_b32_e32 v13, v1
	v_mov_b32_e32 v14, v1
	v_mov_b32_e32 v15, v1
	s_mul_hi_i32 s73, s0, 0x1010
	s_mul_i32 s72, s0, 0x1010
	v_lshl_add_u64 v[194:195], v[188:189], 0, s[4:5]
	v_lshl_add_u64 v[198:199], v[190:191], 0, s[4:5]
	s_add_u32 s89, s1, 0x40000
	s_add_i32 s95, s95, 3
	s_or_b32 s10, s70, 1
	s_addk_i32 s70, 0x5f
	v_add_f32_e32 v158, v1, v24
	s_setprio 1
	v_cvt_pk_bf16_f32 v76, v16, v17
	v_cvt_pk_bf16_f32 v77, v18, v19
	v_cvt_pk_bf16_f32 v78, v20, v21
	v_cvt_pk_bf16_f32 v79, v22, v23
	s_nop 1
	v_mfma_f32_32x32x16_bf16 v[48:63], v[32:35], v[76:79], v[0:15]
	v_mfma_f32_32x32x16_bf16 v[32:47], v[64:67], v[76:79], v[0:15]
	v_mfma_f32_32x32x16_bf16 v[16:31], v[72:75], v[76:79], v[0:15]
	v_mfma_f32_32x32x16_bf16 v[0:15], v[68:71], v[76:79], v[0:15]
	s_setprio 0
	s_mul_hi_i32 s1, s0, 0x808000
	s_mul_i32 s0, s0, 0x808000
	s_or_b32 s0, s0, s2
	v_lshl_add_u64 v[186:187], v[182:183], 0, s[0:1]
	s_mov_b32 s71, 2
	s_mov_b64 s[64:65], 0
	s_mov_b32 s91, 64
	s_waitcnt vmcnt(3)
	ds_write_b128 v209, v[112:115] offset:17408
	s_waitcnt vmcnt(2)
	ds_write_b128 v209, v[116:119] offset:26112
	s_waitcnt vmcnt(1)
	ds_write_b128 v210, v[120:123] offset:55296
	s_waitcnt vmcnt(0)
	ds_write_b128 v211, v[124:127] offset:30720
	v_add_u32_e32 v223, 0x4400, v212
	v_add_u32_e32 v222, 0x5000, v213
	s_waitcnt lgkmcnt(0)
	s_barrier
	s_branch .LBB0_297
.LBB0_296:
	s_add_i32 s71, s71, 1
	s_add_i32 s0, s71, -1
	s_and_b32 s0, s0, 1
	s_mul_i32 s1, s0, 0x5000
	s_mulk_i32 s0, 0x4400
	v_add_u32_e32 v223, s0, v212
	v_add_u32_e32 v222, s1, v213
	s_add_u32 s64, s64, 0x20000
	s_addc_u32 s65, s65, 0
	s_add_i32 s91, s91, 64
	s_cmp_eq_u32 s89, s64
	v_subrev_u32_e32 v153, 64, v153
	s_waitcnt lgkmcnt(0)
	s_barrier
	s_cbranch_scc1 .LBB0_307

; #define LAS __attribute__((address_space(3)))
; #define MFMA32(a, b, c) __builtin_amdgcn_mfma_f32_32x32x16_bf16((a), (b), (c), 0, 0, 0)
; #define VFRAG(ptr, off0, STR) ({ const s16x4 lo_ = vtr((ptr) + (off0)); const s16x4 hi_ = vtr((ptr) + (off0) + 8 * (STR)); (bf16x8){lo_[0], lo_[1], lo_[2], lo_[3], hi_[0], hi_[1], hi_[2], hi_[3]}; })
; __device__ __forceinline__ void diff_unit(const Frame& F, int b, int h, int qi, float lam, int dry) {
;     ...
;             const LAS unsigned char* kb = lds + kra + (it & 1) * DK_BUF;
;             const LAS unsigned char* vb = lds + vra + (it & 1) * DV_BUF;
;             f32x16 s0, s1;
; #pragma unroll
;             for (int r = 0; r < 16; ++r) { s0[r] = 0.f; s1[r] = 0.f; }
;             bf16x8 vpre0 = VFRAG(vb, 0, DV_STR), vpre1 = VFRAG(vb, 64, DV_STR), vpre2 = VFRAG(vb, 128, DV_STR), vpre3 = VFRAG(vb, 192, DV_STR);
;             bf16x8 vprf0 = VFRAG(vb, 16 * DV_STR, DV_STR), vprf1 = VFRAG(vb, 16 * DV_STR + 64, DV_STR);
;             __builtin_amdgcn_s_setprio(1);
; #pragma unroll
;             for (int ks = 0; ks < 4; ++ks) { const bf16x8 k0 = *(const LAS bf16x8*)(kb + ks * 32); s0 = MFMA32(k0, qf[ks], s0); }
;             if (!meta) {
; #pragma unroll
;                 for (int ks = 0; ks < 4; ++ks) { const bf16x8 k1 = *(const LAS bf16x8*)(kb + 32 * DK_STR + ks * 32); s1 = MFMA32(k1, qf[ks], s1); }
;             }
;             __builtin_amdgcn_s_setprio(0);
;             if (meta) {
; #pragma unroll
;                 for (int r = 8; r < 16; ++r) s0[r] = -INFINITY;
; #pragma unroll
;                 for (int r = 0; r < 16; ++r) s1[r] = -INFINITY;
;             } else if (key0 + 63 > tqw) {
; #pragma unroll
;                 for (int r = 0; r < 16; ++r) { const int c = (r & 3) + 8 * (r >> 2), lim = tq - key0 - 4 * hi; if (c > lim) s0[r] = -INFINITY; if (c + 32 > lim) s1[r] = -INFINITY; }
;             }
.LBB0_301:
	ds_read_b128 v[64:67], v223
	ds_read_b128 v[68:71], v223 offset:32
	ds_read_b64_tr_b16 v[148:149], v222 offset:34816
	ds_read_b64_tr_b16 v[144:145], v222 offset:34880
	ds_read_b64_tr_b16 v[140:141], v222 offset:34944
	ds_read_b64_tr_b16 v[136:137], v222 offset:35008
	ds_read_b64_tr_b16 v[150:151], v222 offset:37376
	ds_read_b64_tr_b16 v[146:147], v222 offset:37440
	ds_read_b64_tr_b16 v[142:143], v222 offset:37504
	ds_read_b64_tr_b16 v[138:139], v222 offset:37568
	ds_read_b64_tr_b16 v[128:129], v222 offset:39936
	ds_read_b64_tr_b16 v[130:131], v222 offset:42496
	ds_read_b64_tr_b16 v[134:135], v222 offset:42560
	ds_read_b64_tr_b16 v[132:133], v222 offset:40000
	s_setprio 1
	s_waitcnt lgkmcnt(13)
	v_mfma_f32_32x32x16_bf16 v[80:95], v[64:67], v[96:99], v[238:253]
	s_waitcnt lgkmcnt(12)
	v_mfma_f32_32x32x16_bf16 v[80:95], v[68:71], v[100:103], v[80:95]
	ds_read_b128 v[64:67], v223 offset:64
	ds_read_b128 v[68:71], v223 offset:96
	s_waitcnt lgkmcnt(1)
	v_mfma_f32_32x32x16_bf16 v[80:95], v[64:67], v[104:107], v[80:95]
	ds_read_b128 v[64:67], v223 offset:8704
	ds_read_b128 v[224:227], v223 offset:8736
	s_waitcnt lgkmcnt(2)
	v_mfma_f32_32x32x16_bf16 v[80:95], v[68:71], v[108:111], v[80:95]
	s_waitcnt lgkmcnt(1)
	v_mfma_f32_32x32x16_bf16 v[64:79], v[64:67], v[96:99], v[238:253]
	s_waitcnt lgkmcnt(0)
	v_mfma_f32_32x32x16_bf16 v[64:79], v[224:227], v[100:103], v[64:79]
	ds_read_b128 v[224:227], v223 offset:8768
	ds_read_b128 v[228:231], v223 offset:8800
	s_waitcnt lgkmcnt(1)
	v_mfma_f32_32x32x16_bf16 v[64:79], v[224:227], v[104:107], v[64:79]
	s_waitcnt lgkmcnt(0)
	v_mfma_f32_32x32x16_bf16 v[64:79], v[228:231], v[108:111], v[64:79]
	s_setprio 0
	s_cmp_le_u32 s91, s10
	s_cbranch_scc1 .LBB0_303
	v_cmp_gt_i32_e64 s[60:61], s80, v153
	v_cmp_gt_i32_e64 s[62:63], s81, v153
	v_cmp_gt_i32_e64 s[58:59], s69, v153
	s_and_b64 s[60:61], s[62:63], s[60:61]
	v_cmp_gt_i32_e64 s[56:57], s68, v153
	s_and_b64 s[58:59], s[60:61], s[58:59]
	v_cmp_gt_i32_e64 s[54:55], s87, v153
	s_and_b64 s[56:57], s[58:59], s[56:57]
	v_cmp_gt_i32_e64 s[52:53], s86, v153
	s_and_b64 s[54:55], s[56:57], s[54:55]
	v_cmp_gt_i32_e64 s[50:51], s85, v153
	s_and_b64 s[52:53], s[54:55], s[52:53]
	v_cmp_gt_i32_e64 s[48:49], s79, v153
	s_and_b64 s[50:51], s[52:53], s[50:51]
	v_cmp_gt_i32_e64 s[46:47], s78, v153
	s_and_b64 s[48:49], s[50:51], s[48:49]
	v_cmp_gt_i32_e64 s[44:45], s77, v153
	s_and_b64 s[46:47], s[48:49], s[46:47]
	v_cmp_gt_i32_e64 s[42:43], s76, v153
	s_and_b64 s[44:45], s[46:47], s[44:45]
	v_cmp_gt_i32_e64 s[40:41], s96, v153
	s_and_b64 s[42:43], s[44:45], s[42:43]
	v_cmp_gt_i32_e64 s[38:39], s97, v153
	s_and_b64 s[40:41], s[42:43], s[40:41]
	v_cmp_gt_i32_e64 s[36:37], s93, v153
	s_and_b64 s[38:39], s[40:41], s[38:39]
	v_cmp_gt_i32_e64 s[34:35], s92, v153
	s_and_b64 s[36:37], s[38:39], s[36:37]
	v_cmp_gt_i32_e64 s[30:31], s11, v153
	s_and_b64 s[34:35], s[36:37], s[34:35]
	s_and_b64 s[30:31], s[34:35], s[30:31]
	v_cmp_gt_i32_e64 s[28:29], 10, v153
	v_cndmask_b32_e64 v80, v80, v221, s[30:31]
	v_cmp_gt_i32_e64 s[30:31], 11, v153
	v_cmp_gt_i32_e64 s[26:27], 9, v153
	s_and_b64 s[28:29], s[30:31], s[28:29]
	v_cmp_gt_i32_e64 s[24:25], 8, v153
	s_and_b64 s[26:27], s[28:29], s[26:27]
	v_cmp_gt_i32_e64 s[22:23], 3, v153
	s_and_b64 s[24:25], s[26:27], s[24:25]
	v_cmp_gt_i32_e64 s[20:21], 2, v153
	s_and_b64 s[22:23], s[24:25], s[22:23]
	v_cmp_gt_i32_e64 s[18:19], 1, v153
	s_and_b64 s[20:21], s[22:23], s[20:21]
	v_cmp_lt_u32_e64 s[16:17], s84, v153
	s_and_b64 s[18:19], s[20:21], s[18:19]
	v_cmp_gt_i32_e64 s[14:15], -5, v153
	s_and_b64 s[16:17], s[18:19], s[16:17]
	v_cmp_gt_i32_e64 s[12:13], -6, v153
	s_and_b64 s[14:15], s[16:17], s[14:15]
	v_cmp_gt_i32_e64 s[8:9], -7, v153
	s_and_b64 s[12:13], s[14:15], s[12:13]
	v_cmp_gt_i32_e64 s[6:7], -8, v153
	s_and_b64 s[8:9], s[12:13], s[8:9]
	v_cmp_gt_i32_e64 s[4:5], -13, v153
	s_and_b64 s[6:7], s[8:9], s[6:7]
	v_cmp_gt_i32_e64 s[2:3], -14, v153
	s_and_b64 s[4:5], s[6:7], s[4:5]
	v_cmp_gt_i32_e64 s[0:1], -15, v153
	s_and_b64 s[2:3], s[4:5], s[2:3]
	v_cmp_gt_i32_e32 vcc, -16, v153
	s_and_b64 s[0:1], s[2:3], s[0:1]
	s_and_b64 vcc, s[0:1], vcc
	v_cndmask_b32_e64 v95, v95, v221, s[62:63]
	v_cndmask_b32_e64 v94, v94, v221, s[60:61]
	v_cndmask_b32_e64 v93, v93, v221, s[58:59]
	v_cndmask_b32_e64 v92, v92, v221, s[56:57]
	v_cndmask_b32_e64 v91, v91, v221, s[54:55]
	v_cndmask_b32_e64 v90, v90, v221, s[52:53]
	v_cndmask_b32_e64 v89, v89, v221, s[50:51]
	v_cndmask_b32_e64 v88, v88, v221, s[48:49]
	v_cndmask_b32_e64 v87, v87, v221, s[46:47]
	v_cndmask_b32_e64 v86, v86, v221, s[44:45]
	v_cndmask_b32_e64 v85, v85, v221, s[42:43]
	v_cndmask_b32_e64 v84, v84, v221, s[40:41]
	v_cndmask_b32_e64 v83, v83, v221, s[38:39]
	v_cndmask_b32_e64 v82, v82, v221, s[36:37]
	v_cndmask_b32_e64 v81, v81, v221, s[34:35]
	v_cndmask_b32_e64 v79, v79, v221, s[30:31]
	v_cndmask_b32_e64 v78, v78, v221, s[28:29]
	v_cndmask_b32_e64 v77, v77, v221, s[26:27]
	v_cndmask_b32_e64 v76, v76, v221, s[24:25]
	v_cndmask_b32_e64 v75, v75, v221, s[22:23]
	v_cndmask_b32_e64 v74, v74, v221, s[20:21]
	v_cndmask_b32_e64 v73, v73, v221, s[18:19]
	v_cndmask_b32_e64 v72, v72, v221, s[16:17]
	v_cndmask_b32_e64 v71, v71, v221, s[14:15]
	v_cndmask_b32_e64 v70, v70, v221, s[12:13]
	v_cndmask_b32_e64 v69, v69, v221, s[8:9]
	v_cndmask_b32_e64 v68, v68, v221, s[6:7]
	v_cndmask_b32_e64 v67, v67, v221, s[4:5]
	v_cndmask_b32_e64 v66, v66, v221, s[2:3]
	v_cndmask_b32_e64 v65, v65, v221, s[0:1]
	v_cndmask_b32_e32 v64, v64, v221, vcc

; #define MFMA32(a, b, c) __builtin_amdgcn_mfma_f32_32x32x16_bf16((a), (b), (c), 0, 0, 0)
; #define D_STORE(buf) do { *(LAS u32x4*)(lds + klds + (buf) * DK_BUF) = st0; *(LAS u32x4*)(lds + klds + (buf) * DK_BUF + 32 * DK_STR) = st1; *(LAS u32x4*)(lds + vlds + (buf) * DV_BUF) = st2; *(LAS u32x4*)(lds + vlds + (buf) * DV_BUF + 32 * DV_STR) = st3; } while (0)
; __device__ __forceinline__ void diff_unit(const Frame& F, int b, int h, int qi, float lam, int dry) {
;     ...
;             float ps = 0.f;
; #pragma unroll
;             for (int r = 0; r < 16; ++r) { s0[r] = __builtin_amdgcn_exp2f(s0[r] * LOG2E - ms); ps += s0[r]; }
;             if (!meta) {
; #pragma unroll
;                 for (int r = 0; r < 16; ++r) { s1[r] = __builtin_amdgcn_exp2f(s1[r] * LOG2E - ms); ps += s1[r]; }
;             }
;             lsum += ps;
;             __builtin_amdgcn_s_setprio(1);
;             { const bf16x8 pf = pack_step(s0, 0);
;               O[0] = MFMA32(vpre0, pf, O[0]); O[1] = MFMA32(vpre1, pf, O[1]); O[2] = MFMA32(vpre2, pf, O[2]); O[3] = MFMA32(vpre3, pf, O[3]); }
;     ...
;         if (it + 1 < nt) D_STORE((it + 1) & 1);
;         __syncthreads();
.LBB0_314:
	v_sub_f32_e32 v238, 0, v158
	v_sub_f32_e32 v239, 0, v158
	v_sub_f32_e32 v240, 0, v158
	v_sub_f32_e32 v241, 0, v158
	v_sub_f32_e32 v242, 0, v158
	v_sub_f32_e32 v243, 0, v158
	v_sub_f32_e32 v244, 0, v158
	v_sub_f32_e32 v245, 0, v158
	v_sub_f32_e32 v246, 0, v158
	v_sub_f32_e32 v247, 0, v158
	v_sub_f32_e32 v248, 0, v158
	v_sub_f32_e32 v249, 0, v158
	v_sub_f32_e32 v250, 0, v158
	v_sub_f32_e32 v251, 0, v158
	v_sub_f32_e32 v252, 0, v158
	v_sub_f32_e32 v253, 0, v158
	v_sub_f32_e32 v16, v16, v158
	v_exp_f32_e32 v16, v16
	v_sub_f32_e32 v17, v17, v158
	v_exp_f32_e32 v17, v17
	v_sub_f32_e32 v18, v18, v158
	v_exp_f32_e32 v18, v18
	v_sub_f32_e32 v19, v19, v158
	v_exp_f32_e32 v19, v19
	v_sub_f32_e32 v20, v20, v158
	v_add_f32_e32 v24, 0, v16
	v_exp_f32_e32 v20, v20
	v_sub_f32_e32 v21, v21, v158
	v_add_f32_e32 v24, v17, v24
	v_exp_f32_e32 v21, v21
	v_sub_f32_e32 v22, v22, v158
	v_add_f32_e32 v24, v18, v24
	v_exp_f32_e32 v22, v22
	v_sub_f32_e32 v23, v23, v158
	v_add_f32_e32 v24, v19, v24
	v_exp_f32_e32 v23, v23
	v_sub_f32_e32 v25, 0xff800000, v158
	v_add_f32_e32 v24, v20, v24
	v_exp_f32_e32 v25, v25
	v_add_f32_e32 v24, v21, v24
	v_add_f32_e32 v24, v22, v24
	v_add_f32_e32 v24, v23, v24
	v_add_f32_e32 v24, v25, v24
	v_add_f32_e32 v24, v25, v24
	v_add_f32_e32 v24, v25, v24
	v_add_f32_e32 v24, v25, v24
	v_add_f32_e32 v24, v25, v24
	v_add_f32_e32 v24, v25, v24
	v_add_f32_e32 v24, v25, v24
	s_lshl_b32 s10, s1, 1
	v_add_f32_e32 v24, v25, v24
	v_mov_b32_e32 v2, v1
	v_mov_b32_e32 v3, v1
	v_mov_b32_e32 v4, v1
	v_mov_b32_e32 v5, v1
	v_mov_b32_e32 v6, v1
	v_mov_b32_e32 v7, v1
	v_mov_b32_e32 v8, v1
	v_mov_b32_e32 v9, v1
	v_mov_b32_e32 v10, v1
	v_mov_b32_e32 v11, v1
	v_mov_b32_e32 v12, v1
	v_mov_b32_e32 v13, v1
	v_mov_b32_e32 v14, v1
	v_mov_b32_e32 v15, v1
	s_add_i32 s10, s10, 3
	s_or_b32 s70, s71, 1
	s_addk_i32 s71, 0x5f
	v_add_f32_e32 v153, v1, v24
	s_setprio 1
	v_cvt_pk_bf16_f32 v76, v16, v17
	v_cvt_pk_bf16_f32 v77, v18, v19
	v_cvt_pk_bf16_f32 v78, v20, v21
	v_cvt_pk_bf16_f32 v79, v22, v23
	s_nop 1
	v_mfma_f32_32x32x16_bf16 v[48:63], v[32:35], v[76:79], v[0:15]
	v_mfma_f32_32x32x16_bf16 v[32:47], v[64:67], v[76:79], v[0:15]
	v_mfma_f32_32x32x16_bf16 v[16:31], v[72:75], v[76:79], v[0:15]
	v_mfma_f32_32x32x16_bf16 v[0:15], v[68:71], v[76:79], v[0:15]
	s_setprio 0
	s_lshl_b32 s1, s1, 18
	s_add_u32 s95, s1, 0x40000
	v_add_u32_e32 v185, s0, v217
	s_mov_b32 s2, 2
	s_mov_b64 s[66:67], 0
	s_mov_b32 s3, 64
	s_waitcnt vmcnt(3)
	ds_write_b128 v209, v[112:115] offset:17408
	s_waitcnt vmcnt(2)
	ds_write_b128 v209, v[116:119] offset:26112
	s_waitcnt vmcnt(1)
	ds_write_b128 v210, v[120:123] offset:55296
	s_waitcnt vmcnt(0)
	ds_write_b128 v211, v[124:127] offset:30720
	v_add_u32_e32 v189, 0x4400, v212
	v_add_u32_e32 v188, 0x5000, v213
	s_waitcnt lgkmcnt(0)
	s_barrier
	s_branch .LBB0_316
.LBB0_315:
	s_add_i32 s2, s2, 1
	s_add_i32 s0, s2, -1
	s_and_b32 s0, s0, 1
	s_mul_i32 s1, s0, 0x5000
	s_mulk_i32 s0, 0x4400
	v_add_u32_e32 v189, s0, v212
	v_add_u32_e32 v188, s1, v213
	s_add_u32 s66, s66, 0x20000
	s_addc_u32 s67, s67, 0
	s_add_i32 s3, s3, 64
	s_cmp_eq_u32 s95, s66
	v_subrev_u32_e32 v185, 64, v185
	s_waitcnt lgkmcnt(0)
	s_barrier
	s_cbranch_scc1 .LBB0_326

; #define LAS __attribute__((address_space(3)))
; #define MFMA32(a, b, c) __builtin_amdgcn_mfma_f32_32x32x16_bf16((a), (b), (c), 0, 0, 0)
; #define VFRAG(ptr, off0, STR) ({ const s16x4 lo_ = vtr((ptr) + (off0)); const s16x4 hi_ = vtr((ptr) + (off0) + 8 * (STR)); (bf16x8){lo_[0], lo_[1], lo_[2], lo_[3], hi_[0], hi_[1], hi_[2], hi_[3]}; })
; __device__ __forceinline__ void diff_unit(const Frame& F, int b, int h, int qi, float lam, int dry) {
;     ...
;             const LAS unsigned char* kb = lds + kra + (it & 1) * DK_BUF;
;             const LAS unsigned char* vb = lds + vra + (it & 1) * DV_BUF;
;             f32x16 s0, s1;
; #pragma unroll
;             for (int r = 0; r < 16; ++r) { s0[r] = 0.f; s1[r] = 0.f; }
;             bf16x8 vpre0 = VFRAG(vb, 0, DV_STR), vpre1 = VFRAG(vb, 64, DV_STR), vpre2 = VFRAG(vb, 128, DV_STR), vpre3 = VFRAG(vb, 192, DV_STR);
;             bf16x8 vprf0 = VFRAG(vb, 16 * DV_STR, DV_STR), vprf1 = VFRAG(vb, 16 * DV_STR + 64, DV_STR);
;             __builtin_amdgcn_s_setprio(1);
; #pragma unroll
;             for (int ks = 0; ks < 4; ++ks) { const bf16x8 k0 = *(const LAS bf16x8*)(kb + ks * 32); s0 = MFMA32(k0, qf[ks], s0); }
;             if (!meta) {
; #pragma unroll
;                 for (int ks = 0; ks < 4; ++ks) { const bf16x8 k1 = *(const LAS bf16x8*)(kb + 32 * DK_STR + ks * 32); s1 = MFMA32(k1, qf[ks], s1); }
;             }
;             __builtin_amdgcn_s_setprio(0);
;             if (meta) {
; #pragma unroll
;                 for (int r = 8; r < 16; ++r) s0[r] = -INFINITY;
; #pragma unroll
;                 for (int r = 0; r < 16; ++r) s1[r] = -INFINITY;
;             } else if (key0 + 63 > tqw) {
; #pragma unroll
;                 for (int r = 0; r < 16; ++r) { const int c = (r & 3) + 8 * (r >> 2), lim = tq - key0 - 4 * hi; if (c > lim) s0[r] = -INFINITY; if (c + 32 > lim) s1[r] = -INFINITY; }
;             }
.LBB0_320:
	ds_read_b128 v[64:67], v189
	ds_read_b128 v[68:71], v189 offset:32
	ds_read_b64_tr_b16 v[148:149], v188 offset:34816
	ds_read_b64_tr_b16 v[144:145], v188 offset:34880
	ds_read_b64_tr_b16 v[140:141], v188 offset:34944
	ds_read_b64_tr_b16 v[136:137], v188 offset:35008
	ds_read_b64_tr_b16 v[150:151], v188 offset:37376
	ds_read_b64_tr_b16 v[146:147], v188 offset:37440
	ds_read_b64_tr_b16 v[142:143], v188 offset:37504
	ds_read_b64_tr_b16 v[138:139], v188 offset:37568
	ds_read_b64_tr_b16 v[128:129], v188 offset:39936
	ds_read_b64_tr_b16 v[130:131], v188 offset:42496
	ds_read_b64_tr_b16 v[134:135], v188 offset:42560
	ds_read_b64_tr_b16 v[132:133], v188 offset:40000
	s_setprio 1
	s_waitcnt lgkmcnt(13)
	v_mfma_f32_32x32x16_bf16 v[80:95], v[64:67], v[96:99], v[238:253]
	s_waitcnt lgkmcnt(12)
	v_mfma_f32_32x32x16_bf16 v[80:95], v[68:71], v[100:103], v[80:95]
	ds_read_b128 v[64:67], v189 offset:64
	ds_read_b128 v[68:71], v189 offset:96
	s_waitcnt lgkmcnt(1)
	v_mfma_f32_32x32x16_bf16 v[80:95], v[64:67], v[104:107], v[80:95]
	ds_read_b128 v[64:67], v189 offset:8704
	ds_read_b128 v[190:193], v189 offset:8736
	s_waitcnt lgkmcnt(2)
	v_mfma_f32_32x32x16_bf16 v[80:95], v[68:71], v[108:111], v[80:95]
	s_waitcnt lgkmcnt(1)
	v_mfma_f32_32x32x16_bf16 v[64:79], v[64:67], v[96:99], v[238:253]
	s_waitcnt lgkmcnt(0)
	v_mfma_f32_32x32x16_bf16 v[64:79], v[190:193], v[100:103], v[64:79]
	ds_read_b128 v[190:193], v189 offset:8768
	ds_read_b128 v[194:197], v189 offset:8800
	s_waitcnt lgkmcnt(1)
	v_mfma_f32_32x32x16_bf16 v[64:79], v[190:193], v[104:107], v[64:79]
	s_waitcnt lgkmcnt(0)
	v_mfma_f32_32x32x16_bf16 v[64:79], v[194:197], v[108:111], v[64:79]
	s_setprio 0
	s_cmp_le_u32 s3, s70
	s_cbranch_scc1 .LBB0_322
	v_cmp_gt_i32_e64 s[62:63], s80, v185
	v_cmp_gt_i32_e64 s[64:65], s81, v185
	v_cmp_gt_i32_e64 s[60:61], s69, v185
	s_and_b64 s[62:63], s[64:65], s[62:63]
	v_cmp_gt_i32_e64 s[58:59], s68, v185
	s_and_b64 s[60:61], s[62:63], s[60:61]
	v_cmp_gt_i32_e64 s[56:57], s87, v185
	s_and_b64 s[58:59], s[60:61], s[58:59]
	v_cmp_gt_i32_e64 s[54:55], s86, v185
	s_and_b64 s[56:57], s[58:59], s[56:57]
	v_cmp_gt_i32_e64 s[52:53], s85, v185
	s_and_b64 s[54:55], s[56:57], s[54:55]
	v_cmp_gt_i32_e64 s[50:51], s79, v185
	s_and_b64 s[52:53], s[54:55], s[52:53]
	v_cmp_gt_i32_e64 s[48:49], s78, v185
	s_and_b64 s[50:51], s[52:53], s[50:51]
	v_cmp_gt_i32_e64 s[46:47], s77, v185
	s_and_b64 s[48:49], s[50:51], s[48:49]
	v_cmp_gt_i32_e64 s[44:45], s76, v185
	s_and_b64 s[46:47], s[48:49], s[46:47]
	v_cmp_gt_i32_e64 s[42:43], s96, v185
	s_and_b64 s[44:45], s[46:47], s[44:45]
	v_cmp_gt_i32_e64 s[40:41], s97, v185
	s_and_b64 s[42:43], s[44:45], s[42:43]
	v_cmp_gt_i32_e64 s[38:39], s93, v185
	s_and_b64 s[40:41], s[42:43], s[40:41]
	v_cmp_gt_i32_e64 s[36:37], s92, v185
	s_and_b64 s[38:39], s[40:41], s[38:39]
	v_cmp_gt_i32_e64 s[34:35], s11, v185
	s_and_b64 s[36:37], s[38:39], s[36:37]
	s_and_b64 s[34:35], s[36:37], s[34:35]
	v_cmp_gt_i32_e64 s[30:31], 10, v185
	v_cndmask_b32_e64 v80, v80, v221, s[34:35]
	v_cmp_gt_i32_e64 s[34:35], 11, v185
	v_cmp_gt_i32_e64 s[28:29], 9, v185
	s_and_b64 s[30:31], s[34:35], s[30:31]
	v_cmp_gt_i32_e64 s[26:27], 8, v185
	s_and_b64 s[28:29], s[30:31], s[28:29]
	v_cmp_gt_i32_e64 s[24:25], 3, v185
	s_and_b64 s[26:27], s[28:29], s[26:27]
	v_cmp_gt_i32_e64 s[22:23], 2, v185
	s_and_b64 s[24:25], s[26:27], s[24:25]
	v_cmp_gt_i32_e64 s[20:21], 1, v185
	s_and_b64 s[22:23], s[24:25], s[22:23]
	v_cmp_lt_u32_e64 s[18:19], s84, v185
	s_and_b64 s[20:21], s[22:23], s[20:21]
	v_cmp_gt_i32_e64 s[16:17], -5, v185
	s_and_b64 s[18:19], s[20:21], s[18:19]
	v_cmp_gt_i32_e64 s[14:15], -6, v185
	s_and_b64 s[16:17], s[18:19], s[16:17]
	v_cmp_gt_i32_e64 s[12:13], -7, v185
	s_and_b64 s[14:15], s[16:17], s[14:15]
	v_cmp_gt_i32_e64 s[8:9], -8, v185
	s_and_b64 s[12:13], s[14:15], s[12:13]
	v_cmp_gt_i32_e64 s[6:7], -13, v185
	s_and_b64 s[8:9], s[12:13], s[8:9]
	v_cmp_gt_i32_e64 s[4:5], -14, v185
	s_and_b64 s[6:7], s[8:9], s[6:7]
	v_cmp_gt_i32_e64 s[0:1], -15, v185
	s_and_b64 s[4:5], s[6:7], s[4:5]
	v_cmp_gt_i32_e32 vcc, -16, v185
	s_and_b64 s[0:1], s[4:5], s[0:1]
	s_and_b64 vcc, s[0:1], vcc
	v_cndmask_b32_e64 v95, v95, v221, s[64:65]
	v_cndmask_b32_e64 v94, v94, v221, s[62:63]
	v_cndmask_b32_e64 v93, v93, v221, s[60:61]
	v_cndmask_b32_e64 v92, v92, v221, s[58:59]
	v_cndmask_b32_e64 v91, v91, v221, s[56:57]
	v_cndmask_b32_e64 v90, v90, v221, s[54:55]
	v_cndmask_b32_e64 v89, v89, v221, s[52:53]
	v_cndmask_b32_e64 v88, v88, v221, s[50:51]
	v_cndmask_b32_e64 v87, v87, v221, s[48:49]
	v_cndmask_b32_e64 v86, v86, v221, s[46:47]
	v_cndmask_b32_e64 v85, v85, v221, s[44:45]
	v_cndmask_b32_e64 v84, v84, v221, s[42:43]
	v_cndmask_b32_e64 v83, v83, v221, s[40:41]
	v_cndmask_b32_e64 v82, v82, v221, s[38:39]
	v_cndmask_b32_e64 v81, v81, v221, s[36:37]
	v_cndmask_b32_e64 v79, v79, v221, s[34:35]
	v_cndmask_b32_e64 v78, v78, v221, s[30:31]
	v_cndmask_b32_e64 v77, v77, v221, s[28:29]
	v_cndmask_b32_e64 v76, v76, v221, s[26:27]
	v_cndmask_b32_e64 v75, v75, v221, s[24:25]
	v_cndmask_b32_e64 v74, v74, v221, s[22:23]
	v_cndmask_b32_e64 v73, v73, v221, s[20:21]
	v_cndmask_b32_e64 v72, v72, v221, s[18:19]
	v_cndmask_b32_e64 v71, v71, v221, s[16:17]
	v_cndmask_b32_e64 v70, v70, v221, s[14:15]
	v_cndmask_b32_e64 v69, v69, v221, s[12:13]
	v_cndmask_b32_e64 v68, v68, v221, s[8:9]
	v_cndmask_b32_e64 v67, v67, v221, s[6:7]
	v_cndmask_b32_e64 v66, v66, v221, s[4:5]
	v_cndmask_b32_e64 v65, v65, v221, s[0:1]
	v_cndmask_b32_e32 v64, v64, v221, vcc
